# in-proj q/k epilogue: rope-table loads of each step hoisted above the previous step's stores so the counted wait no longer includes store acks (on top of v6)
# speedup vs baseline: 1.0460x; 1.0052x over previous
; DI unsigned cvtpk(float lo, float hi) { f32x2 v = {lo, hi}; bf16x2_t b = __builtin_convertvector(v, bf16x2_t); return __builtin_bit_cast(unsigned, b); }
;     DI void operator()(const f32x4 (&acc)[2][2][4][2], const pg8::Unit& u, int wr, int wc, int fr, int fq) const {
;     ...
;                     const int row = u.pm * 256 + ai * 128 + wr * 64 + m * 16 + fr;
;                     f32x4 v[2][2]; float ss = 0.f;
; #pragma unroll
;                     for (int bj = 0; bj < 2; ++bj)
; #pragma unroll
;                         for (int n = 0; n < 2; ++n) { v[bj][n] = acc[ai][bj][m][n]; const f32x4 q = v[bj][n] * v[bj][n]; ss += (q[0] + q[1]) + (q[2] + q[3]); }
;                     ss += swz_xor(ss, 16); ss = sum_x32(ss);
;                     const float rinv = rsqrtf(ss * (1.0f / 64.0f) + EPS) * qs;
; #pragma unroll
;                     for (int bj = 0; bj < 2; ++bj)
; #pragma unroll
;                         for (int n = 0; n < 2; ++n) v[bj][n] = v[bj][n] * rinv * w[bj][n];
;                     if (!is_ctx) {
;                         const int t = row & (SEQ - 1), pos = (fq >> 1) ? (t & 63) : (t >> 6);
;                         const f32x4* tp = (const f32x4*)(rope + (size_t)(pos * 16 + 8 * (fq & 1)) * 2);
; #pragma unroll
;                         for (int n = 0; n < 2; ++n) {
;                             const f32x4 cs0 = tp[2 * n], cs1 = tp[2 * n + 1];
;                             const f32x4 cv = {cs0[0], cs0[2], cs1[0], cs1[2]}, sv = {cs0[1], cs0[3], cs1[1], cs1[3]};
;                             const f32x4 x1 = v[0][n], x2 = v[1][n];
;                             v[0][n] = x1 * cv - x2 * sv; v[1][n] = x2 * cv + x1 * sv;
;                         }
;                     }
;                     bf16_t* rp = P + (size_t)row * DIN + colw;
; #pragma unroll
;                     for (int bj = 0; bj < 2; ++bj) { u32x4 o; o.x = cvtpk(v[bj][0][0], v[bj][0][1]); o.y = cvtpk(v[bj][0][2], v[bj][0][3]); o.z = cvtpk(v[bj][1][0], v[bj][1][1]); o.w = cvtpk(v[bj][1][2], v[bj][1][3]);
;                         *(u32x4*)(rp + 16 * bj) = o; }
.LBB0_251:
	v_or_b32_e32 v160, s31, v152
	v_mov_b64_e32 v[162:163], s[50:51]
	v_mad_i64_i32 v[162:163], s[6:7], v160, s87, v[162:163]
	v_lshl_add_u64 v[162:163], v[222:223], 1, v[162:163]
	v_cvt_pk_bf16_f32 v132, v132, v133
	v_cvt_pk_bf16_f32 v133, v134, v135
	v_cvt_pk_bf16_f32 v134, v128, v129
	v_cvt_pk_bf16_f32 v135, v130, v131
	v_cvt_pk_bf16_f32 v128, v138, v139
	v_cvt_pk_bf16_f32 v129, v136, v137
	v_cvt_pk_bf16_f32 v130, v142, v143
	v_cvt_pk_bf16_f32 v131, v140, v141
	s_andn2_b64 vcc, exec, s[72:73]
	s_cbranch_vccnz .Lrope_skip_1
	v_or_b32_e32 v200, 16, v160
	v_mov_b32_e32 v201, s59
	v_cndmask_b32_e64 v200, v200, v201, s[36:37]
	v_lshlrev_b32_e32 v200, 4, v200
	v_and_or_b32 v200, v200, s8, v155
	v_lshlrev_b32_e32 v200, 3, v200
	global_load_dwordx4 v[184:187], v200, s[56:57] offset:32
	global_load_dwordx4 v[188:191], v200, s[56:57] offset:48
	global_load_dwordx4 v[192:195], v200, s[56:57]
	global_load_dwordx4 v[196:199], v200, s[56:57] offset:16
.Lrope_skip_1:
	global_store_dwordx4 v[162:163], v[128:131], off offset:32
	global_store_dwordx4 v[162:163], v[132:135], off
	v_pk_mul_f32 v[136:137], v[114:115], v[114:115]
	v_pk_mul_f32 v[128:129], v[126:127], v[126:127]
	v_pk_mul_f32 v[130:131], v[124:125], v[124:125]
	v_pk_mul_f32 v[138:139], v[112:113], v[112:113]
	v_pk_mov_b32 v[132:133], v[130:131], v[128:129] op_sel:[1,0]
	v_mov_b32_e32 v131, v129
	v_pk_add_f32 v[128:129], v[132:133], v[130:131]
	v_pk_mul_f32 v[130:131], v[122:123], v[122:123]
	v_pk_mul_f32 v[132:133], v[120:121], v[120:121]
	v_pk_add_f32 v[128:129], v[128:129], v[128:129] op_sel:[0,1] op_sel_hi:[1,0]
	v_pk_mov_b32 v[134:135], v[132:133], v[130:131] op_sel:[1,0]
	v_mov_b32_e32 v133, v131
	v_pk_add_f32 v[130:131], v[134:135], v[132:133]
	v_pk_mul_f32 v[132:133], v[118:119], v[118:119]
	v_pk_add_f32 v[130:131], v[130:131], v[130:131] op_sel:[0,1] op_sel_hi:[1,0]
	v_pk_mul_f32 v[134:135], v[116:117], v[116:117]
	v_add_f32_e32 v132, v132, v133
	v_add_f32_e32 v134, v134, v135
	v_mov_b32_e32 v129, v138
	v_mov_b32_e32 v131, v139
	v_mov_b32_e32 v135, v136
	v_mov_b32_e32 v133, v137
	v_pk_add_f32 v[128:129], v[128:129], v[130:131]
	v_pk_add_f32 v[130:131], v[134:135], v[132:133]
	v_readlane_b32 s24, v254, 18
	v_pk_add_f32 v[128:129], v[128:129], v[130:131]
	v_readlane_b32 s25, v254, 19
	v_add_f32_e32 v128, v128, v129
	ds_swizzle_b32 v129, v128 offset:swizzle(SWAP,16)
	s_waitcnt lgkmcnt(0)
	v_add_f32_e32 v128, v128, v129
	v_mov_b32_e32 v129, v128
	s_nop 1
	v_permlane32_swap_b32_e32 v128, v129
	v_add_f32_e32 v128, v128, v129
	v_fmamk_f32 v128, v128, 0x3c800000, v221
	v_cmp_gt_f32_e32 vcc, s85, v128
	v_mul_f32_e32 v129, 0x4b800000, v128
	s_nop 0
	v_cndmask_b32_e32 v128, v128, v129, vcc
	v_rsq_f32_e32 v128, v128
	s_nop 0
	v_mul_f32_e32 v129, 0x45800000, v128
	v_cndmask_b32_e32 v128, v128, v129, vcc
	v_mul_f32_e32 v128, v159, v128
	v_pk_mul_f32 v[130:131], v[116:117], v[128:129] op_sel_hi:[1,0]
	v_pk_mul_f32 v[124:125], v[124:125], v[128:129] op_sel_hi:[1,0]
	v_pk_mul_f32 v[126:127], v[126:127], v[128:129] op_sel_hi:[1,0]
	v_pk_mul_f32 v[120:121], v[120:121], v[128:129] op_sel_hi:[1,0]
	v_pk_mul_f32 v[122:123], v[122:123], v[128:129] op_sel_hi:[1,0]
	v_pk_mul_f32 v[116:117], v[118:119], v[128:129] op_sel_hi:[1,0]
	v_pk_mul_f32 v[118:119], v[100:101], v[130:131]
	v_pk_mul_f32 v[130:131], v[112:113], v[128:129] op_sel_hi:[1,0]
	v_pk_mul_f32 v[112:113], v[114:115], v[128:129] op_sel_hi:[1,0]
	v_cndmask_b32_e64 v129, 0, 1, s[72:73]
	v_pk_mul_f32 v[126:127], v[110:111], v[126:127]
	v_pk_mul_f32 v[124:125], v[108:109], v[124:125]
	v_pk_mul_f32 v[122:123], v[106:107], v[122:123]
	v_pk_mul_f32 v[120:121], v[104:105], v[120:121]
	v_pk_mul_f32 v[116:117], v[102:103], v[116:117]
	v_pk_mul_f32 v[112:113], v[98:99], v[112:113]
	v_pk_mul_f32 v[114:115], v[96:97], v[130:131]
	v_or_b32_e32 v128, 16, v160
	v_cmp_ne_u32_e64 s[38:39], 1, v129
	s_andn2_b64 vcc, exec, s[72:73]
	s_cbranch_vccnz .LBB0_253
	v_mov_b32_e32 v129, s59
	v_cndmask_b32_e64 v129, v128, v129, s[36:37]
	v_lshlrev_b32_e32 v129, 4, v129
	v_and_or_b32 v129, v129, s8, v155
	v_lshlrev_b32_e32 v129, 3, v129
	s_waitcnt vmcnt(2)
	v_mov_b32_e32 v130, v184
	v_mov_b32_e32 v131, v185
	v_mov_b32_e32 v132, v186
	v_mov_b32_e32 v133, v187
	v_mov_b32_e32 v134, v188
	v_mov_b32_e32 v135, v189
	v_mov_b32_e32 v136, v190
	v_mov_b32_e32 v137, v191
	v_mov_b32_e32 v138, v192
	v_mov_b32_e32 v139, v193
	v_mov_b32_e32 v140, v194
	v_mov_b32_e32 v141, v195
	v_mov_b32_e32 v162, v196
	v_mov_b32_e32 v163, v197
	v_mov_b32_e32 v164, v198
	v_mov_b32_e32 v165, v199
	s_waitcnt vmcnt(2)
	v_mov_b32_e32 v166, v139
	v_mov_b32_e32 v167, v141
	v_pk_mul_f32 v[168:169], v[118:119], v[166:167]
	s_waitcnt vmcnt(2)
	v_mov_b32_e32 v170, v163
	v_mov_b32_e32 v171, v165
	v_mov_b32_e32 v139, v140
	v_pk_mul_f32 v[142:143], v[116:117], v[170:171]
	v_mov_b32_e32 v163, v164
	v_pk_fma_f32 v[140:141], v[124:125], v[138:139], v[168:169] neg_lo:[0,0,1] neg_hi:[0,0,1]
	v_pk_mul_f32 v[118:119], v[118:119], v[138:139]
	v_mov_b32_e32 v138, v131
	v_mov_b32_e32 v139, v133
	v_pk_fma_f32 v[142:143], v[126:127], v[162:163], v[142:143] neg_lo:[0,0,1] neg_hi:[0,0,1]
	v_pk_mul_f32 v[116:117], v[116:117], v[162:163]
	v_pk_fma_f32 v[118:119], v[124:125], v[166:167], v[118:119]
	v_pk_mul_f32 v[124:125], v[114:115], v[138:139]
	v_mov_b32_e32 v162, v135
	v_mov_b32_e32 v163, v137
	v_mov_b32_e32 v135, v136
	v_mov_b32_e32 v131, v132
	v_pk_fma_f32 v[116:117], v[126:127], v[170:171], v[116:117]
	v_pk_mul_f32 v[126:127], v[112:113], v[162:163]
	v_pk_fma_f32 v[124:125], v[120:121], v[130:131], v[124:125] neg_lo:[0,0,1] neg_hi:[0,0,1]
	v_pk_mul_f32 v[114:115], v[114:115], v[130:131]
	v_pk_mul_f32 v[112:113], v[112:113], v[134:135]
	v_pk_fma_f32 v[126:127], v[122:123], v[134:135], v[126:127] neg_lo:[0,0,1] neg_hi:[0,0,1]
	v_pk_fma_f32 v[112:113], v[122:123], v[162:163], v[112:113]
	v_pk_fma_f32 v[114:115], v[120:121], v[138:139], v[114:115]
	v_mov_b64_e32 v[120:121], v[124:125]
	v_mov_b64_e32 v[122:123], v[126:127]
	v_mov_b64_e32 v[124:125], v[140:141]
	v_mov_b64_e32 v[126:127], v[142:143]
; DI unsigned cvtpk(float lo, float hi) { f32x2 v = {lo, hi}; bf16x2_t b = __builtin_convertvector(v, bf16x2_t); return __builtin_bit_cast(unsigned, b); }
;     DI void operator()(const f32x4 (&acc)[2][2][4][2], const pg8::Unit& u, int wr, int wc, int fr, int fq) const {
;     ...
;                     const int row = u.pm * 256 + ai * 128 + wr * 64 + m * 16 + fr;
;                     f32x4 v[2][2]; float ss = 0.f;
; #pragma unroll
;                     for (int bj = 0; bj < 2; ++bj)
; #pragma unroll
;                         for (int n = 0; n < 2; ++n) { v[bj][n] = acc[ai][bj][m][n]; const f32x4 q = v[bj][n] * v[bj][n]; ss += (q[0] + q[1]) + (q[2] + q[3]); }
;                     ss += swz_xor(ss, 16); ss = sum_x32(ss);
;                     const float rinv = rsqrtf(ss * (1.0f / 64.0f) + EPS) * qs;
; #pragma unroll
;                     for (int bj = 0; bj < 2; ++bj)
; #pragma unroll
;                         for (int n = 0; n < 2; ++n) v[bj][n] = v[bj][n] * rinv * w[bj][n];
;                     if (!is_ctx) {
;                         const int t = row & (SEQ - 1), pos = (fq >> 1) ? (t & 63) : (t >> 6);
;                         const f32x4* tp = (const f32x4*)(rope + (size_t)(pos * 16 + 8 * (fq & 1)) * 2);
; #pragma unroll
;                         for (int n = 0; n < 2; ++n) {
;                             const f32x4 cs0 = tp[2 * n], cs1 = tp[2 * n + 1];
;                             const f32x4 cv = {cs0[0], cs0[2], cs1[0], cs1[2]}, sv = {cs0[1], cs0[3], cs1[1], cs1[3]};
;                             const f32x4 x1 = v[0][n], x2 = v[1][n];
;                             v[0][n] = x1 * cv - x2 * sv; v[1][n] = x2 * cv + x1 * sv;
;                         }
;                     }
;                     bf16_t* rp = P + (size_t)row * DIN + colw;
; #pragma unroll
;                     for (int bj = 0; bj < 2; ++bj) { u32x4 o; o.x = cvtpk(v[bj][0][0], v[bj][0][1]); o.y = cvtpk(v[bj][0][2], v[bj][0][3]); o.z = cvtpk(v[bj][1][0], v[bj][1][1]); o.w = cvtpk(v[bj][1][2], v[bj][1][3]);
;                         *(u32x4*)(rp + 16 * bj) = o; }
.LBB0_253:
	v_mov_b64_e32 v[130:131], s[50:51]
	v_cvt_pk_bf16_f32 v124, v124, v125
	v_cvt_pk_bf16_f32 v125, v126, v127
	v_cvt_pk_bf16_f32 v126, v120, v121
	v_cvt_pk_bf16_f32 v120, v114, v115
	v_cvt_pk_bf16_f32 v121, v112, v113
	v_pk_mul_f32 v[112:113], v[94:95], v[94:95]
	v_pk_mul_f32 v[114:115], v[92:93], v[92:93]
	v_mad_i64_i32 v[128:129], s[6:7], v128, s87, v[130:131]
	v_cvt_pk_bf16_f32 v118, v118, v119
	v_cvt_pk_bf16_f32 v119, v116, v117
	v_pk_mov_b32 v[116:117], v[114:115], v[112:113] op_sel:[1,0]
	v_mov_b32_e32 v115, v113
	v_lshl_add_u64 v[128:129], v[222:223], 1, v[128:129]
	v_pk_add_f32 v[112:113], v[116:117], v[114:115]
	v_pk_mul_f32 v[114:115], v[90:91], v[90:91]
	v_pk_mul_f32 v[116:117], v[88:89], v[88:89]
	s_andn2_b64 vcc, exec, s[72:73]
	s_cbranch_vccnz .Lrope_skip_2
	v_or_b32_e32 v200, 32, v160
	v_mov_b32_e32 v201, s59
	v_cndmask_b32_e64 v200, v200, v201, s[36:37]
	v_lshlrev_b32_e32 v200, 4, v200
	v_and_or_b32 v200, v200, s8, v155
	v_lshlrev_b32_e32 v200, 3, v200
	global_load_dwordx4 v[184:187], v200, s[56:57] offset:32
	global_load_dwordx4 v[188:191], v200, s[56:57] offset:48
	global_load_dwordx4 v[192:195], v200, s[56:57]
	global_load_dwordx4 v[196:199], v200, s[56:57] offset:16
.Lrope_skip_2:
	global_store_dwordx4 v[128:129], v[118:121], off offset:32
	v_cvt_pk_bf16_f32 v127, v122, v123
	v_pk_add_f32 v[112:113], v[112:113], v[112:113] op_sel:[0,1] op_sel_hi:[1,0]
	v_pk_mov_b32 v[118:119], v[116:117], v[114:115] op_sel:[1,0]
	v_mov_b32_e32 v117, v115
	v_pk_add_f32 v[114:115], v[118:119], v[116:117]
	v_pk_mul_f32 v[116:117], v[86:87], v[86:87]
	v_pk_add_f32 v[114:115], v[114:115], v[114:115] op_sel:[0,1] op_sel_hi:[1,0]
	v_pk_mul_f32 v[118:119], v[84:85], v[84:85]
	v_pk_mul_f32 v[120:121], v[82:83], v[82:83]
	v_pk_mul_f32 v[122:123], v[80:81], v[80:81]
	v_add_f32_e32 v118, v118, v119
	v_add_f32_e32 v116, v116, v117
	v_mov_b32_e32 v113, v122
	v_mov_b32_e32 v115, v123
	v_mov_b32_e32 v119, v120
	v_mov_b32_e32 v117, v121
	v_pk_add_f32 v[112:113], v[112:113], v[114:115]
	v_pk_add_f32 v[114:115], v[118:119], v[116:117]
	global_store_dwordx4 v[128:129], v[124:127], off
	v_pk_add_f32 v[112:113], v[112:113], v[114:115]
	s_nop 0
	v_add_f32_e32 v112, v112, v113
	ds_swizzle_b32 v113, v112 offset:swizzle(SWAP,16)
	s_waitcnt lgkmcnt(0)
	v_add_f32_e32 v112, v112, v113
	v_mov_b32_e32 v113, v112
	s_nop 1
	v_permlane32_swap_b32_e32 v112, v113
	v_add_f32_e32 v112, v112, v113
	v_fmamk_f32 v112, v112, 0x3c800000, v221
	v_cmp_gt_f32_e32 vcc, s85, v112
	v_mul_f32_e32 v113, 0x4b800000, v112
	s_nop 0
	v_cndmask_b32_e32 v112, v112, v113, vcc
	v_rsq_f32_e32 v112, v112
	s_nop 0
	v_mul_f32_e32 v113, 0x45800000, v112
	v_cndmask_b32_e32 v112, v112, v113, vcc
	v_mul_f32_e32 v112, v159, v112
	v_pk_mul_f32 v[114:115], v[84:85], v[112:113] op_sel_hi:[1,0]
	v_pk_mul_f32 v[92:93], v[92:93], v[112:113] op_sel_hi:[1,0]
	v_pk_mul_f32 v[94:95], v[94:95], v[112:113] op_sel_hi:[1,0]
	v_pk_mul_f32 v[88:89], v[88:89], v[112:113] op_sel_hi:[1,0]
	v_pk_mul_f32 v[90:91], v[90:91], v[112:113] op_sel_hi:[1,0]
	v_pk_mul_f32 v[84:85], v[86:87], v[112:113] op_sel_hi:[1,0]
	v_pk_mul_f32 v[86:87], v[100:101], v[114:115]
	v_pk_mul_f32 v[114:115], v[80:81], v[112:113] op_sel_hi:[1,0]
	v_pk_mul_f32 v[80:81], v[82:83], v[112:113] op_sel_hi:[1,0]
	v_pk_mul_f32 v[94:95], v[110:111], v[94:95]
	v_pk_mul_f32 v[92:93], v[108:109], v[92:93]
	v_pk_mul_f32 v[90:91], v[106:107], v[90:91]
	v_pk_mul_f32 v[88:89], v[104:105], v[88:89]
	v_pk_mul_f32 v[84:85], v[102:103], v[84:85]
	v_pk_mul_f32 v[80:81], v[98:99], v[80:81]
	v_pk_mul_f32 v[82:83], v[96:97], v[114:115]
	v_or_b32_e32 v112, 32, v160
	s_and_b64 vcc, exec, s[38:39]
	s_cbranch_vccnz .LBB0_255
	v_mov_b32_e32 v113, s59
	v_cndmask_b32_e64 v113, v112, v113, s[36:37]
	v_lshlrev_b32_e32 v113, 4, v113
	v_and_or_b32 v113, v113, s8, v155
	v_lshlrev_b32_e32 v113, 3, v113
	s_waitcnt vmcnt(2)
	v_mov_b32_e32 v114, v184
	v_mov_b32_e32 v115, v185
	v_mov_b32_e32 v116, v186
	v_mov_b32_e32 v117, v187
	v_mov_b32_e32 v118, v188
	v_mov_b32_e32 v119, v189
	v_mov_b32_e32 v120, v190
	v_mov_b32_e32 v121, v191
	v_mov_b32_e32 v122, v192
	v_mov_b32_e32 v123, v193
	v_mov_b32_e32 v124, v194
	v_mov_b32_e32 v125, v195
	v_mov_b32_e32 v126, v196
	v_mov_b32_e32 v127, v197
	v_mov_b32_e32 v128, v198
	v_mov_b32_e32 v129, v199
	s_waitcnt vmcnt(2)
	v_mov_b32_e32 v132, v123
	v_mov_b32_e32 v133, v125
	v_pk_mul_f32 v[134:135], v[86:87], v[132:133]
	v_mov_b32_e32 v123, v124
	s_waitcnt vmcnt(2)
	v_mov_b32_e32 v136, v127
	v_mov_b32_e32 v137, v129
	v_mov_b32_e32 v127, v128
	v_pk_fma_f32 v[128:129], v[92:93], v[122:123], v[134:135] neg_lo:[0,0,1] neg_hi:[0,0,1]
	v_pk_mul_f32 v[86:87], v[86:87], v[122:123]
	v_mov_b32_e32 v122, v115
	v_mov_b32_e32 v123, v117
	v_pk_mul_f32 v[130:131], v[84:85], v[136:137]
	v_pk_mul_f32 v[84:85], v[84:85], v[126:127]
	v_pk_fma_f32 v[86:87], v[92:93], v[132:133], v[86:87]
	v_pk_mul_f32 v[92:93], v[82:83], v[122:123]
	v_mov_b32_e32 v124, v119
	v_mov_b32_e32 v125, v121
	v_mov_b32_e32 v119, v120
	v_mov_b32_e32 v115, v116
	v_pk_fma_f32 v[130:131], v[94:95], v[126:127], v[130:131] neg_lo:[0,0,1] neg_hi:[0,0,1]
	v_pk_fma_f32 v[84:85], v[94:95], v[136:137], v[84:85]
	v_pk_mul_f32 v[94:95], v[80:81], v[124:125]
	v_pk_fma_f32 v[92:93], v[88:89], v[114:115], v[92:93] neg_lo:[0,0,1] neg_hi:[0,0,1]
	v_pk_mul_f32 v[82:83], v[82:83], v[114:115]
	v_pk_mul_f32 v[80:81], v[80:81], v[118:119]
	v_pk_fma_f32 v[94:95], v[90:91], v[118:119], v[94:95] neg_lo:[0,0,1] neg_hi:[0,0,1]
	v_pk_fma_f32 v[80:81], v[90:91], v[124:125], v[80:81]
	v_pk_fma_f32 v[82:83], v[88:89], v[122:123], v[82:83]
	v_mov_b64_e32 v[88:89], v[92:93]
	v_mov_b64_e32 v[90:91], v[94:95]
	v_mov_b64_e32 v[92:93], v[128:129]
	v_mov_b64_e32 v[94:95], v[130:131]
; DI unsigned cvtpk(float lo, float hi) { f32x2 v = {lo, hi}; bf16x2_t b = __builtin_convertvector(v, bf16x2_t); return __builtin_bit_cast(unsigned, b); }
;     DI void operator()(const f32x4 (&acc)[2][2][4][2], const pg8::Unit& u, int wr, int wc, int fr, int fq) const {
;     ...
;                     const int row = u.pm * 256 + ai * 128 + wr * 64 + m * 16 + fr;
;                     f32x4 v[2][2]; float ss = 0.f;
; #pragma unroll
;                     for (int bj = 0; bj < 2; ++bj)
; #pragma unroll
;                         for (int n = 0; n < 2; ++n) { v[bj][n] = acc[ai][bj][m][n]; const f32x4 q = v[bj][n] * v[bj][n]; ss += (q[0] + q[1]) + (q[2] + q[3]); }
;                     ss += swz_xor(ss, 16); ss = sum_x32(ss);
;                     const float rinv = rsqrtf(ss * (1.0f / 64.0f) + EPS) * qs;
; #pragma unroll
;                     for (int bj = 0; bj < 2; ++bj)
; #pragma unroll
;                         for (int n = 0; n < 2; ++n) v[bj][n] = v[bj][n] * rinv * w[bj][n];
;                     if (!is_ctx) {
;                         const int t = row & (SEQ - 1), pos = (fq >> 1) ? (t & 63) : (t >> 6);
;                         const f32x4* tp = (const f32x4*)(rope + (size_t)(pos * 16 + 8 * (fq & 1)) * 2);
; #pragma unroll
;                         for (int n = 0; n < 2; ++n) {
;                             const f32x4 cs0 = tp[2 * n], cs1 = tp[2 * n + 1];
;                             const f32x4 cv = {cs0[0], cs0[2], cs1[0], cs1[2]}, sv = {cs0[1], cs0[3], cs1[1], cs1[3]};
;                             const f32x4 x1 = v[0][n], x2 = v[1][n];
;                             v[0][n] = x1 * cv - x2 * sv; v[1][n] = x2 * cv + x1 * sv;
;                         }
;                     }
;                     bf16_t* rp = P + (size_t)row * DIN + colw;
; #pragma unroll
;                     for (int bj = 0; bj < 2; ++bj) { u32x4 o; o.x = cvtpk(v[bj][0][0], v[bj][0][1]); o.y = cvtpk(v[bj][0][2], v[bj][0][3]); o.z = cvtpk(v[bj][1][0], v[bj][1][1]); o.w = cvtpk(v[bj][1][2], v[bj][1][3]);
;                         *(u32x4*)(rp + 16 * bj) = o; }
.LBB0_255:
	v_mov_b64_e32 v[114:115], s[50:51]
	v_cvt_pk_bf16_f32 v92, v92, v93
	v_cvt_pk_bf16_f32 v93, v94, v95
	v_cvt_pk_bf16_f32 v94, v88, v89
	v_cvt_pk_bf16_f32 v88, v82, v83
	v_cvt_pk_bf16_f32 v89, v80, v81
	v_pk_mul_f32 v[80:81], v[78:79], v[78:79]
	v_pk_mul_f32 v[82:83], v[76:77], v[76:77]
	v_mad_i64_i32 v[112:113], s[6:7], v112, s87, v[114:115]
	v_cvt_pk_bf16_f32 v86, v86, v87
	v_cvt_pk_bf16_f32 v87, v84, v85
	v_pk_mov_b32 v[84:85], v[82:83], v[80:81] op_sel:[1,0]
	v_mov_b32_e32 v83, v81
	v_lshl_add_u64 v[112:113], v[222:223], 1, v[112:113]
	v_pk_add_f32 v[80:81], v[84:85], v[82:83]
	v_pk_mul_f32 v[82:83], v[74:75], v[74:75]
	v_pk_mul_f32 v[84:85], v[72:73], v[72:73]
	s_andn2_b64 vcc, exec, s[72:73]
	s_cbranch_vccnz .Lrope_skip_3
	v_or_b32_e32 v200, 48, v160
	v_mov_b32_e32 v201, s59
	v_cndmask_b32_e64 v200, v200, v201, s[36:37]
	v_lshlrev_b32_e32 v200, 4, v200
	v_and_or_b32 v200, v200, s8, v155
	v_lshlrev_b32_e32 v200, 3, v200
	global_load_dwordx4 v[184:187], v200, s[56:57] offset:32
	global_load_dwordx4 v[188:191], v200, s[56:57] offset:48
	global_load_dwordx4 v[192:195], v200, s[56:57]
	global_load_dwordx4 v[196:199], v200, s[56:57] offset:16
.Lrope_skip_3:
	global_store_dwordx4 v[112:113], v[86:89], off offset:32
	v_cvt_pk_bf16_f32 v95, v90, v91
	v_pk_add_f32 v[80:81], v[80:81], v[80:81] op_sel:[0,1] op_sel_hi:[1,0]
	v_pk_mov_b32 v[86:87], v[84:85], v[82:83] op_sel:[1,0]
	v_mov_b32_e32 v85, v83
	v_pk_add_f32 v[82:83], v[86:87], v[84:85]
	v_pk_mul_f32 v[84:85], v[70:71], v[70:71]
	v_pk_add_f32 v[82:83], v[82:83], v[82:83] op_sel:[0,1] op_sel_hi:[1,0]
	v_pk_mul_f32 v[86:87], v[68:69], v[68:69]
	v_pk_mul_f32 v[88:89], v[66:67], v[66:67]
	v_pk_mul_f32 v[90:91], v[64:65], v[64:65]
	v_add_f32_e32 v86, v86, v87
	v_add_f32_e32 v84, v84, v85
	v_mov_b32_e32 v81, v90
	v_mov_b32_e32 v83, v91
	v_mov_b32_e32 v87, v88
	v_mov_b32_e32 v85, v89
	v_pk_add_f32 v[80:81], v[80:81], v[82:83]
	v_pk_add_f32 v[82:83], v[86:87], v[84:85]
	global_store_dwordx4 v[112:113], v[92:95], off
	v_pk_add_f32 v[80:81], v[80:81], v[82:83]
	s_nop 0
	v_add_f32_e32 v80, v80, v81
	ds_swizzle_b32 v81, v80 offset:swizzle(SWAP,16)
	s_waitcnt lgkmcnt(0)
	v_add_f32_e32 v80, v80, v81
	v_mov_b32_e32 v81, v80
	s_nop 1
	v_permlane32_swap_b32_e32 v80, v81
	v_add_f32_e32 v80, v80, v81
	v_fmamk_f32 v80, v80, 0x3c800000, v221
	v_cmp_gt_f32_e32 vcc, s85, v80
	v_mul_f32_e32 v81, 0x4b800000, v80
	s_nop 0
	v_cndmask_b32_e32 v80, v80, v81, vcc
	v_rsq_f32_e32 v80, v80
	s_nop 0
	v_mul_f32_e32 v81, 0x45800000, v80
	v_cndmask_b32_e32 v80, v80, v81, vcc
	v_mul_f32_e32 v80, v159, v80
	v_pk_mul_f32 v[82:83], v[68:69], v[80:81] op_sel_hi:[1,0]
	v_pk_mul_f32 v[76:77], v[76:77], v[80:81] op_sel_hi:[1,0]
	v_pk_mul_f32 v[78:79], v[78:79], v[80:81] op_sel_hi:[1,0]
	v_pk_mul_f32 v[72:73], v[72:73], v[80:81] op_sel_hi:[1,0]
	v_pk_mul_f32 v[74:75], v[74:75], v[80:81] op_sel_hi:[1,0]
	v_pk_mul_f32 v[68:69], v[70:71], v[80:81] op_sel_hi:[1,0]
	v_pk_mul_f32 v[70:71], v[100:101], v[82:83]
	v_pk_mul_f32 v[82:83], v[64:65], v[80:81] op_sel_hi:[1,0]
	v_pk_mul_f32 v[64:65], v[66:67], v[80:81] op_sel_hi:[1,0]
	v_pk_mul_f32 v[78:79], v[110:111], v[78:79]
	v_pk_mul_f32 v[76:77], v[108:109], v[76:77]
	v_pk_mul_f32 v[74:75], v[106:107], v[74:75]
	v_pk_mul_f32 v[72:73], v[104:105], v[72:73]
	v_pk_mul_f32 v[68:69], v[102:103], v[68:69]
	v_pk_mul_f32 v[64:65], v[98:99], v[64:65]
	v_pk_mul_f32 v[66:67], v[96:97], v[82:83]
	v_or_b32_e32 v80, 48, v160
	s_and_b64 vcc, exec, s[38:39]
	s_cbranch_vccnz .LBB0_257
	v_mov_b32_e32 v81, s59
	v_cndmask_b32_e64 v81, v80, v81, s[36:37]
	v_lshlrev_b32_e32 v81, 4, v81
	v_and_or_b32 v81, v81, s8, v155
	v_lshlrev_b32_e32 v81, 3, v81
	s_waitcnt vmcnt(2)
	v_mov_b32_e32 v82, v184
	v_mov_b32_e32 v83, v185
	v_mov_b32_e32 v84, v186
	v_mov_b32_e32 v85, v187
	v_mov_b32_e32 v86, v188
	v_mov_b32_e32 v87, v189
	v_mov_b32_e32 v88, v190
	v_mov_b32_e32 v89, v191
	v_mov_b32_e32 v90, v192
	v_mov_b32_e32 v91, v193
	v_mov_b32_e32 v92, v194
	v_mov_b32_e32 v93, v195
	v_mov_b32_e32 v112, v196
	v_mov_b32_e32 v113, v197
	v_mov_b32_e32 v114, v198
	v_mov_b32_e32 v115, v199
	s_waitcnt vmcnt(2)
	v_mov_b32_e32 v116, v91
	v_mov_b32_e32 v117, v93
	v_pk_mul_f32 v[118:119], v[70:71], v[116:117]
	s_waitcnt vmcnt(2)
	v_mov_b32_e32 v120, v113
	v_mov_b32_e32 v121, v115
	v_mov_b32_e32 v91, v92
	v_pk_mul_f32 v[94:95], v[68:69], v[120:121]
	v_mov_b32_e32 v113, v114
	v_pk_fma_f32 v[92:93], v[76:77], v[90:91], v[118:119] neg_lo:[0,0,1] neg_hi:[0,0,1]
	v_pk_mul_f32 v[70:71], v[70:71], v[90:91]
	v_mov_b32_e32 v90, v83
	v_mov_b32_e32 v91, v85
	v_pk_fma_f32 v[94:95], v[78:79], v[112:113], v[94:95] neg_lo:[0,0,1] neg_hi:[0,0,1]
	v_pk_mul_f32 v[68:69], v[68:69], v[112:113]
	v_pk_fma_f32 v[70:71], v[76:77], v[116:117], v[70:71]
	v_pk_mul_f32 v[76:77], v[66:67], v[90:91]
	v_mov_b32_e32 v112, v87
	v_mov_b32_e32 v113, v89
	v_mov_b32_e32 v87, v88
	v_mov_b32_e32 v83, v84
	v_pk_fma_f32 v[68:69], v[78:79], v[120:121], v[68:69]
	v_pk_mul_f32 v[78:79], v[64:65], v[112:113]
	v_pk_fma_f32 v[76:77], v[72:73], v[82:83], v[76:77] neg_lo:[0,0,1] neg_hi:[0,0,1]
	v_pk_mul_f32 v[66:67], v[66:67], v[82:83]
	v_pk_mul_f32 v[64:65], v[64:65], v[86:87]
	v_pk_fma_f32 v[78:79], v[74:75], v[86:87], v[78:79] neg_lo:[0,0,1] neg_hi:[0,0,1]
	v_pk_fma_f32 v[64:65], v[74:75], v[112:113], v[64:65]
	v_pk_fma_f32 v[66:67], v[72:73], v[90:91], v[66:67]
	v_mov_b64_e32 v[72:73], v[76:77]
	v_mov_b64_e32 v[74:75], v[78:79]
	v_mov_b64_e32 v[76:77], v[92:93]
	v_mov_b64_e32 v[78:79], v[94:95]

; DI unsigned cvtpk(float lo, float hi) { f32x2 v = {lo, hi}; bf16x2_t b = __builtin_convertvector(v, bf16x2_t); return __builtin_bit_cast(unsigned, b); }
;     DI void operator()(const f32x4 (&acc)[2][2][4][2], const pg8::Unit& u, int wr, int wc, int fr, int fq) const {
;     ...
;                     const int row = u.pm * 256 + ai * 128 + wr * 64 + m * 16 + fr;
;                     f32x4 v[2][2]; float ss = 0.f;
; #pragma unroll
;                     for (int bj = 0; bj < 2; ++bj)
; #pragma unroll
;                         for (int n = 0; n < 2; ++n) { v[bj][n] = acc[ai][bj][m][n]; const f32x4 q = v[bj][n] * v[bj][n]; ss += (q[0] + q[1]) + (q[2] + q[3]); }
;                     ss += swz_xor(ss, 16); ss = sum_x32(ss);
;                     const float rinv = rsqrtf(ss * (1.0f / 64.0f) + EPS) * qs;
; #pragma unroll
;                     for (int bj = 0; bj < 2; ++bj)
; #pragma unroll
;                         for (int n = 0; n < 2; ++n) v[bj][n] = v[bj][n] * rinv * w[bj][n];
;                     if (!is_ctx) {
;                         const int t = row & (SEQ - 1), pos = (fq >> 1) ? (t & 63) : (t >> 6);
;                         const f32x4* tp = (const f32x4*)(rope + (size_t)(pos * 16 + 8 * (fq & 1)) * 2);
; #pragma unroll
;                         for (int n = 0; n < 2; ++n) {
;                             const f32x4 cs0 = tp[2 * n], cs1 = tp[2 * n + 1];
;                             const f32x4 cv = {cs0[0], cs0[2], cs1[0], cs1[2]}, sv = {cs0[1], cs0[3], cs1[1], cs1[3]};
;                             const f32x4 x1 = v[0][n], x2 = v[1][n];
;                             v[0][n] = x1 * cv - x2 * sv; v[1][n] = x2 * cv + x1 * sv;
;                         }
;                     }
;                     bf16_t* rp = P + (size_t)row * DIN + colw;
; #pragma unroll
;                     for (int bj = 0; bj < 2; ++bj) { u32x4 o; o.x = cvtpk(v[bj][0][0], v[bj][0][1]); o.y = cvtpk(v[bj][0][2], v[bj][0][3]); o.z = cvtpk(v[bj][1][0], v[bj][1][1]); o.w = cvtpk(v[bj][1][2], v[bj][1][3]);
;                         *(u32x4*)(rp + 16 * bj) = o; }
.LBB0_259:
	v_mov_b64_e32 v[66:67], s[50:51]
	v_cvt_pk_bf16_f32 v60, v60, v61
	v_cvt_pk_bf16_f32 v61, v62, v63
	v_cvt_pk_bf16_f32 v62, v56, v57
	v_cvt_pk_bf16_f32 v56, v50, v51
	v_cvt_pk_bf16_f32 v57, v48, v49
	v_pk_mul_f32 v[48:49], v[46:47], v[46:47]
	v_pk_mul_f32 v[50:51], v[44:45], v[44:45]
	v_mad_i64_i32 v[66:67], s[6:7], v64, s87, v[66:67]
	v_cvt_pk_bf16_f32 v54, v54, v55
	v_cvt_pk_bf16_f32 v55, v52, v53
	v_pk_mov_b32 v[52:53], v[50:51], v[48:49] op_sel:[1,0]
	v_mov_b32_e32 v51, v49
	v_lshl_add_u64 v[66:67], v[222:223], 1, v[66:67]
	v_pk_add_f32 v[48:49], v[52:53], v[50:51]
	v_pk_mul_f32 v[50:51], v[42:43], v[42:43]
	v_pk_mul_f32 v[52:53], v[40:41], v[40:41]
	s_andn2_b64 vcc, exec, s[72:73]
	s_cbranch_vccnz .Lrope_skip_5
	v_or_b32_e32 v200, 16, v64
	v_mov_b32_e32 v201, s31
	v_cndmask_b32_e64 v200, v200, v201, s[36:37]
	v_lshlrev_b32_e32 v200, 4, v200
	v_and_or_b32 v200, v200, s8, v155
	v_lshlrev_b32_e32 v200, 3, v200
	global_load_dwordx4 v[184:187], v200, s[56:57] offset:32
	global_load_dwordx4 v[188:191], v200, s[56:57] offset:48
	global_load_dwordx4 v[192:195], v200, s[56:57]
	global_load_dwordx4 v[196:199], v200, s[56:57] offset:16
.Lrope_skip_5:
	global_store_dwordx4 v[66:67], v[54:57], off offset:32
	v_cvt_pk_bf16_f32 v63, v58, v59
	v_pk_add_f32 v[48:49], v[48:49], v[48:49] op_sel:[0,1] op_sel_hi:[1,0]
	v_pk_mov_b32 v[54:55], v[52:53], v[50:51] op_sel:[1,0]
	v_mov_b32_e32 v53, v51
	v_pk_add_f32 v[50:51], v[54:55], v[52:53]
	v_pk_mul_f32 v[52:53], v[38:39], v[38:39]
	v_pk_add_f32 v[50:51], v[50:51], v[50:51] op_sel:[0,1] op_sel_hi:[1,0]
	v_pk_mul_f32 v[54:55], v[36:37], v[36:37]
	v_pk_mul_f32 v[56:57], v[34:35], v[34:35]
	v_pk_mul_f32 v[58:59], v[32:33], v[32:33]
	v_add_f32_e32 v54, v54, v55
	v_add_f32_e32 v52, v52, v53
	v_mov_b32_e32 v49, v58
	v_mov_b32_e32 v51, v59
	v_mov_b32_e32 v55, v56
	v_mov_b32_e32 v53, v57
	v_pk_add_f32 v[48:49], v[48:49], v[50:51]
	v_pk_add_f32 v[50:51], v[54:55], v[52:53]
	global_store_dwordx4 v[66:67], v[60:63], off
	v_pk_add_f32 v[48:49], v[48:49], v[50:51]
	s_nop 0
	v_add_f32_e32 v48, v48, v49
	ds_swizzle_b32 v49, v48 offset:swizzle(SWAP,16)
	s_waitcnt lgkmcnt(0)
	v_add_f32_e32 v48, v48, v49
	v_mov_b32_e32 v49, v48
	s_nop 1
	v_permlane32_swap_b32_e32 v48, v49
	v_add_f32_e32 v48, v48, v49
	v_fmamk_f32 v48, v48, 0x3c800000, v221
	v_cmp_gt_f32_e32 vcc, s85, v48
	v_mul_f32_e32 v49, 0x4b800000, v48
	s_nop 0
	v_cndmask_b32_e32 v48, v48, v49, vcc
	v_rsq_f32_e32 v48, v48
	s_nop 0
	v_mul_f32_e32 v49, 0x45800000, v48
	v_cndmask_b32_e32 v48, v48, v49, vcc
	v_mul_f32_e32 v48, v159, v48
	v_pk_mul_f32 v[50:51], v[36:37], v[48:49] op_sel_hi:[1,0]
	v_pk_mul_f32 v[44:45], v[44:45], v[48:49] op_sel_hi:[1,0]
	v_pk_mul_f32 v[46:47], v[46:47], v[48:49] op_sel_hi:[1,0]
	v_pk_mul_f32 v[40:41], v[40:41], v[48:49] op_sel_hi:[1,0]
	v_pk_mul_f32 v[42:43], v[42:43], v[48:49] op_sel_hi:[1,0]
	v_pk_mul_f32 v[36:37], v[38:39], v[48:49] op_sel_hi:[1,0]
	v_pk_mul_f32 v[38:39], v[100:101], v[50:51]
	v_pk_mul_f32 v[50:51], v[32:33], v[48:49] op_sel_hi:[1,0]
	v_pk_mul_f32 v[32:33], v[34:35], v[48:49] op_sel_hi:[1,0]
	v_pk_mul_f32 v[46:47], v[110:111], v[46:47]
	v_pk_mul_f32 v[44:45], v[108:109], v[44:45]
	v_pk_mul_f32 v[42:43], v[106:107], v[42:43]
	v_pk_mul_f32 v[40:41], v[104:105], v[40:41]
	v_pk_mul_f32 v[36:37], v[102:103], v[36:37]
	v_pk_mul_f32 v[32:33], v[98:99], v[32:33]
	v_pk_mul_f32 v[34:35], v[96:97], v[50:51]
	v_or_b32_e32 v48, 16, v64
	s_and_b64 vcc, exec, s[38:39]
	s_cbranch_vccnz .LBB0_261
	v_mov_b32_e32 v49, s31
	v_cndmask_b32_e64 v49, v48, v49, s[36:37]
	v_lshlrev_b32_e32 v49, 4, v49
	v_and_or_b32 v49, v49, s8, v155
	v_lshlrev_b32_e32 v49, 3, v49
	s_waitcnt vmcnt(2)
	v_mov_b32_e32 v50, v184
	v_mov_b32_e32 v51, v185
	v_mov_b32_e32 v52, v186
	v_mov_b32_e32 v53, v187
	v_mov_b32_e32 v54, v188
	v_mov_b32_e32 v55, v189
	v_mov_b32_e32 v56, v190
	v_mov_b32_e32 v57, v191
	v_mov_b32_e32 v58, v192
	v_mov_b32_e32 v59, v193
	v_mov_b32_e32 v60, v194
	v_mov_b32_e32 v61, v195
	v_mov_b32_e32 v66, v196
	v_mov_b32_e32 v67, v197
	v_mov_b32_e32 v68, v198
	v_mov_b32_e32 v69, v199
	s_waitcnt vmcnt(2)
	v_mov_b32_e32 v70, v59
	v_mov_b32_e32 v71, v61
	v_pk_mul_f32 v[72:73], v[38:39], v[70:71]
	s_waitcnt vmcnt(2)
	v_mov_b32_e32 v74, v67
	v_mov_b32_e32 v75, v69
	v_mov_b32_e32 v59, v60
	v_pk_mul_f32 v[62:63], v[36:37], v[74:75]
	v_mov_b32_e32 v67, v68
	v_pk_fma_f32 v[60:61], v[44:45], v[58:59], v[72:73] neg_lo:[0,0,1] neg_hi:[0,0,1]
	v_pk_mul_f32 v[38:39], v[38:39], v[58:59]
	v_mov_b32_e32 v58, v51
	v_mov_b32_e32 v59, v53
	v_pk_fma_f32 v[62:63], v[46:47], v[66:67], v[62:63] neg_lo:[0,0,1] neg_hi:[0,0,1]
	v_pk_mul_f32 v[36:37], v[36:37], v[66:67]
	v_pk_fma_f32 v[38:39], v[44:45], v[70:71], v[38:39]
	v_pk_mul_f32 v[44:45], v[34:35], v[58:59]
	v_mov_b32_e32 v66, v55
	v_mov_b32_e32 v67, v57
	v_mov_b32_e32 v55, v56
	v_mov_b32_e32 v51, v52
	v_pk_fma_f32 v[36:37], v[46:47], v[74:75], v[36:37]
	v_pk_mul_f32 v[46:47], v[32:33], v[66:67]
	v_pk_fma_f32 v[44:45], v[40:41], v[50:51], v[44:45] neg_lo:[0,0,1] neg_hi:[0,0,1]
	v_pk_mul_f32 v[34:35], v[34:35], v[50:51]
	v_pk_mul_f32 v[32:33], v[32:33], v[54:55]
	v_pk_fma_f32 v[46:47], v[42:43], v[54:55], v[46:47] neg_lo:[0,0,1] neg_hi:[0,0,1]
	v_pk_fma_f32 v[32:33], v[42:43], v[66:67], v[32:33]
	v_pk_fma_f32 v[34:35], v[40:41], v[58:59], v[34:35]
	v_mov_b64_e32 v[40:41], v[44:45]
	v_mov_b64_e32 v[42:43], v[46:47]
	v_mov_b64_e32 v[44:45], v[60:61]
	v_mov_b64_e32 v[46:47], v[62:63]
; DI unsigned cvtpk(float lo, float hi) { f32x2 v = {lo, hi}; bf16x2_t b = __builtin_convertvector(v, bf16x2_t); return __builtin_bit_cast(unsigned, b); }
;     DI void operator()(const f32x4 (&acc)[2][2][4][2], const pg8::Unit& u, int wr, int wc, int fr, int fq) const {
;     ...
;                     const int row = u.pm * 256 + ai * 128 + wr * 64 + m * 16 + fr;
;                     f32x4 v[2][2]; float ss = 0.f;
; #pragma unroll
;                     for (int bj = 0; bj < 2; ++bj)
; #pragma unroll
;                         for (int n = 0; n < 2; ++n) { v[bj][n] = acc[ai][bj][m][n]; const f32x4 q = v[bj][n] * v[bj][n]; ss += (q[0] + q[1]) + (q[2] + q[3]); }
;                     ss += swz_xor(ss, 16); ss = sum_x32(ss);
;                     const float rinv = rsqrtf(ss * (1.0f / 64.0f) + EPS) * qs;
; #pragma unroll
;                     for (int bj = 0; bj < 2; ++bj)
; #pragma unroll
;                         for (int n = 0; n < 2; ++n) v[bj][n] = v[bj][n] * rinv * w[bj][n];
;                     if (!is_ctx) {
;                         const int t = row & (SEQ - 1), pos = (fq >> 1) ? (t & 63) : (t >> 6);
;                         const f32x4* tp = (const f32x4*)(rope + (size_t)(pos * 16 + 8 * (fq & 1)) * 2);
; #pragma unroll
;                         for (int n = 0; n < 2; ++n) {
;                             const f32x4 cs0 = tp[2 * n], cs1 = tp[2 * n + 1];
;                             const f32x4 cv = {cs0[0], cs0[2], cs1[0], cs1[2]}, sv = {cs0[1], cs0[3], cs1[1], cs1[3]};
;                             const f32x4 x1 = v[0][n], x2 = v[1][n];
;                             v[0][n] = x1 * cv - x2 * sv; v[1][n] = x2 * cv + x1 * sv;
;                         }
;                     }
;                     bf16_t* rp = P + (size_t)row * DIN + colw;
; #pragma unroll
;                     for (int bj = 0; bj < 2; ++bj) { u32x4 o; o.x = cvtpk(v[bj][0][0], v[bj][0][1]); o.y = cvtpk(v[bj][0][2], v[bj][0][3]); o.z = cvtpk(v[bj][1][0], v[bj][1][1]); o.w = cvtpk(v[bj][1][2], v[bj][1][3]);
;                         *(u32x4*)(rp + 16 * bj) = o; }
.LBB0_261:
	v_mov_b64_e32 v[50:51], s[50:51]
	v_cvt_pk_bf16_f32 v44, v44, v45
	v_cvt_pk_bf16_f32 v45, v46, v47
	v_cvt_pk_bf16_f32 v46, v40, v41
	v_cvt_pk_bf16_f32 v40, v34, v35
	v_cvt_pk_bf16_f32 v41, v32, v33
	v_pk_mul_f32 v[32:33], v[30:31], v[30:31]
	v_pk_mul_f32 v[34:35], v[28:29], v[28:29]
	v_mad_i64_i32 v[48:49], s[6:7], v48, s87, v[50:51]
	v_cvt_pk_bf16_f32 v38, v38, v39
	v_cvt_pk_bf16_f32 v39, v36, v37
	v_pk_mov_b32 v[36:37], v[34:35], v[32:33] op_sel:[1,0]
	v_mov_b32_e32 v35, v33
	v_lshl_add_u64 v[48:49], v[222:223], 1, v[48:49]
	v_pk_add_f32 v[32:33], v[36:37], v[34:35]
	v_pk_mul_f32 v[34:35], v[26:27], v[26:27]
	v_pk_mul_f32 v[36:37], v[24:25], v[24:25]
	s_andn2_b64 vcc, exec, s[72:73]
	s_cbranch_vccnz .Lrope_skip_6
	v_or_b32_e32 v200, 32, v64
	v_mov_b32_e32 v201, s31
	v_cndmask_b32_e64 v200, v200, v201, s[36:37]
	v_lshlrev_b32_e32 v200, 4, v200
	v_and_or_b32 v200, v200, s8, v155
	v_lshlrev_b32_e32 v200, 3, v200
	global_load_dwordx4 v[184:187], v200, s[56:57] offset:32
	global_load_dwordx4 v[188:191], v200, s[56:57] offset:48
	global_load_dwordx4 v[192:195], v200, s[56:57]
	global_load_dwordx4 v[196:199], v200, s[56:57] offset:16
.Lrope_skip_6:
	global_store_dwordx4 v[48:49], v[38:41], off offset:32
	v_cvt_pk_bf16_f32 v47, v42, v43
	v_pk_add_f32 v[32:33], v[32:33], v[32:33] op_sel:[0,1] op_sel_hi:[1,0]
	v_pk_mov_b32 v[38:39], v[36:37], v[34:35] op_sel:[1,0]
	v_mov_b32_e32 v37, v35
	v_pk_add_f32 v[34:35], v[38:39], v[36:37]
	v_pk_mul_f32 v[36:37], v[22:23], v[22:23]
	v_pk_add_f32 v[34:35], v[34:35], v[34:35] op_sel:[0,1] op_sel_hi:[1,0]
	v_pk_mul_f32 v[38:39], v[20:21], v[20:21]
	v_pk_mul_f32 v[40:41], v[18:19], v[18:19]
	v_pk_mul_f32 v[42:43], v[16:17], v[16:17]
	v_add_f32_e32 v38, v38, v39
	v_add_f32_e32 v36, v36, v37
	v_mov_b32_e32 v33, v42
	v_mov_b32_e32 v35, v43
	v_mov_b32_e32 v39, v40
	v_mov_b32_e32 v37, v41
	v_pk_add_f32 v[32:33], v[32:33], v[34:35]
	v_pk_add_f32 v[34:35], v[38:39], v[36:37]
	global_store_dwordx4 v[48:49], v[44:47], off
	v_pk_add_f32 v[32:33], v[32:33], v[34:35]
	s_nop 0
	v_add_f32_e32 v32, v32, v33
	ds_swizzle_b32 v33, v32 offset:swizzle(SWAP,16)
	s_waitcnt lgkmcnt(0)
	v_add_f32_e32 v32, v32, v33
	v_mov_b32_e32 v33, v32
	s_nop 1
	v_permlane32_swap_b32_e32 v32, v33
	v_add_f32_e32 v32, v32, v33
	v_fmamk_f32 v32, v32, 0x3c800000, v221
	v_cmp_gt_f32_e32 vcc, s85, v32
	v_mul_f32_e32 v33, 0x4b800000, v32
	s_nop 0
	v_cndmask_b32_e32 v32, v32, v33, vcc
	v_rsq_f32_e32 v32, v32
	s_nop 0
	v_mul_f32_e32 v33, 0x45800000, v32
	v_cndmask_b32_e32 v32, v32, v33, vcc
	v_mul_f32_e32 v32, v159, v32
	v_pk_mul_f32 v[34:35], v[20:21], v[32:33] op_sel_hi:[1,0]
	v_pk_mul_f32 v[28:29], v[28:29], v[32:33] op_sel_hi:[1,0]
	v_pk_mul_f32 v[30:31], v[30:31], v[32:33] op_sel_hi:[1,0]
	v_pk_mul_f32 v[24:25], v[24:25], v[32:33] op_sel_hi:[1,0]
	v_pk_mul_f32 v[26:27], v[26:27], v[32:33] op_sel_hi:[1,0]
	v_pk_mul_f32 v[20:21], v[22:23], v[32:33] op_sel_hi:[1,0]
	v_pk_mul_f32 v[22:23], v[100:101], v[34:35]
	v_pk_mul_f32 v[34:35], v[16:17], v[32:33] op_sel_hi:[1,0]
	v_pk_mul_f32 v[16:17], v[18:19], v[32:33] op_sel_hi:[1,0]
	v_pk_mul_f32 v[30:31], v[110:111], v[30:31]
	v_pk_mul_f32 v[28:29], v[108:109], v[28:29]
	v_pk_mul_f32 v[26:27], v[106:107], v[26:27]
	v_pk_mul_f32 v[24:25], v[104:105], v[24:25]
	v_pk_mul_f32 v[20:21], v[102:103], v[20:21]
	v_pk_mul_f32 v[16:17], v[98:99], v[16:17]
	v_pk_mul_f32 v[18:19], v[96:97], v[34:35]
	v_or_b32_e32 v32, 32, v64
	s_and_b64 vcc, exec, s[38:39]
	s_cbranch_vccnz .LBB0_263
	v_mov_b32_e32 v33, s31
	v_cndmask_b32_e64 v33, v32, v33, s[36:37]
	v_lshlrev_b32_e32 v33, 4, v33
	v_and_or_b32 v33, v33, s8, v155
	v_lshlrev_b32_e32 v33, 3, v33
	s_waitcnt vmcnt(2)
	v_mov_b32_e32 v34, v184
	v_mov_b32_e32 v35, v185
	v_mov_b32_e32 v36, v186
	v_mov_b32_e32 v37, v187
	v_mov_b32_e32 v38, v188
	v_mov_b32_e32 v39, v189
	v_mov_b32_e32 v40, v190
	v_mov_b32_e32 v41, v191
	v_mov_b32_e32 v42, v192
	v_mov_b32_e32 v43, v193
	v_mov_b32_e32 v44, v194
	v_mov_b32_e32 v45, v195
	v_mov_b32_e32 v46, v196
	v_mov_b32_e32 v47, v197
	v_mov_b32_e32 v48, v198
	v_mov_b32_e32 v49, v199
	s_waitcnt vmcnt(2)
	v_mov_b32_e32 v52, v43
	v_mov_b32_e32 v53, v45
	v_pk_mul_f32 v[54:55], v[22:23], v[52:53]
	v_mov_b32_e32 v43, v44
	s_waitcnt vmcnt(2)
	v_mov_b32_e32 v56, v47
	v_mov_b32_e32 v57, v49
	v_mov_b32_e32 v47, v48
	v_pk_fma_f32 v[48:49], v[28:29], v[42:43], v[54:55] neg_lo:[0,0,1] neg_hi:[0,0,1]
	v_pk_mul_f32 v[22:23], v[22:23], v[42:43]
	v_mov_b32_e32 v42, v35
	v_mov_b32_e32 v43, v37
	v_pk_mul_f32 v[50:51], v[20:21], v[56:57]
	v_pk_mul_f32 v[20:21], v[20:21], v[46:47]
	v_pk_fma_f32 v[22:23], v[28:29], v[52:53], v[22:23]
	v_pk_mul_f32 v[28:29], v[18:19], v[42:43]
	v_mov_b32_e32 v44, v39
	v_mov_b32_e32 v45, v41
	v_mov_b32_e32 v39, v40
	v_mov_b32_e32 v35, v36
	v_pk_fma_f32 v[50:51], v[30:31], v[46:47], v[50:51] neg_lo:[0,0,1] neg_hi:[0,0,1]
	v_pk_fma_f32 v[20:21], v[30:31], v[56:57], v[20:21]
	v_pk_mul_f32 v[30:31], v[16:17], v[44:45]
	v_pk_fma_f32 v[28:29], v[24:25], v[34:35], v[28:29] neg_lo:[0,0,1] neg_hi:[0,0,1]
	v_pk_mul_f32 v[18:19], v[18:19], v[34:35]
	v_pk_mul_f32 v[16:17], v[16:17], v[38:39]
	v_pk_fma_f32 v[30:31], v[26:27], v[38:39], v[30:31] neg_lo:[0,0,1] neg_hi:[0,0,1]
	v_pk_fma_f32 v[16:17], v[26:27], v[44:45], v[16:17]
	v_pk_fma_f32 v[18:19], v[24:25], v[42:43], v[18:19]
	v_mov_b64_e32 v[24:25], v[28:29]
	v_mov_b64_e32 v[26:27], v[30:31]
	v_mov_b64_e32 v[28:29], v[48:49]
	v_mov_b64_e32 v[30:31], v[50:51]
; DI unsigned cvtpk(float lo, float hi) { f32x2 v = {lo, hi}; bf16x2_t b = __builtin_convertvector(v, bf16x2_t); return __builtin_bit_cast(unsigned, b); }
;     DI void operator()(const f32x4 (&acc)[2][2][4][2], const pg8::Unit& u, int wr, int wc, int fr, int fq) const {
;     ...
;                     const int row = u.pm * 256 + ai * 128 + wr * 64 + m * 16 + fr;
;                     f32x4 v[2][2]; float ss = 0.f;
; #pragma unroll
;                     for (int bj = 0; bj < 2; ++bj)
; #pragma unroll
;                         for (int n = 0; n < 2; ++n) { v[bj][n] = acc[ai][bj][m][n]; const f32x4 q = v[bj][n] * v[bj][n]; ss += (q[0] + q[1]) + (q[2] + q[3]); }
;                     ss += swz_xor(ss, 16); ss = sum_x32(ss);
;                     const float rinv = rsqrtf(ss * (1.0f / 64.0f) + EPS) * qs;
; #pragma unroll
;                     for (int bj = 0; bj < 2; ++bj)
; #pragma unroll
;                         for (int n = 0; n < 2; ++n) v[bj][n] = v[bj][n] * rinv * w[bj][n];
;                     if (!is_ctx) {
;                         const int t = row & (SEQ - 1), pos = (fq >> 1) ? (t & 63) : (t >> 6);
;                         const f32x4* tp = (const f32x4*)(rope + (size_t)(pos * 16 + 8 * (fq & 1)) * 2);
; #pragma unroll
;                         for (int n = 0; n < 2; ++n) {
;                             const f32x4 cs0 = tp[2 * n], cs1 = tp[2 * n + 1];
;                             const f32x4 cv = {cs0[0], cs0[2], cs1[0], cs1[2]}, sv = {cs0[1], cs0[3], cs1[1], cs1[3]};
;                             const f32x4 x1 = v[0][n], x2 = v[1][n];
;                             v[0][n] = x1 * cv - x2 * sv; v[1][n] = x2 * cv + x1 * sv;
;                         }
;                     }
;                     bf16_t* rp = P + (size_t)row * DIN + colw;
; #pragma unroll
;                     for (int bj = 0; bj < 2; ++bj) { u32x4 o; o.x = cvtpk(v[bj][0][0], v[bj][0][1]); o.y = cvtpk(v[bj][0][2], v[bj][0][3]); o.z = cvtpk(v[bj][1][0], v[bj][1][1]); o.w = cvtpk(v[bj][1][2], v[bj][1][3]);
;                         *(u32x4*)(rp + 16 * bj) = o; }
.LBB0_263:
	v_mov_b64_e32 v[34:35], s[50:51]
	v_cvt_pk_bf16_f32 v28, v28, v29
	v_cvt_pk_bf16_f32 v29, v30, v31
	v_cvt_pk_bf16_f32 v30, v24, v25
	v_cvt_pk_bf16_f32 v24, v18, v19
	v_cvt_pk_bf16_f32 v25, v16, v17
	v_pk_mul_f32 v[16:17], v[14:15], v[14:15]
	v_pk_mul_f32 v[18:19], v[12:13], v[12:13]
	v_mad_i64_i32 v[32:33], s[6:7], v32, s87, v[34:35]
	v_cvt_pk_bf16_f32 v22, v22, v23
	v_cvt_pk_bf16_f32 v23, v20, v21
	v_pk_mov_b32 v[20:21], v[18:19], v[16:17] op_sel:[1,0]
	v_mov_b32_e32 v19, v17
	v_lshl_add_u64 v[32:33], v[222:223], 1, v[32:33]
	v_pk_add_f32 v[16:17], v[20:21], v[18:19]
	v_pk_mul_f32 v[18:19], v[10:11], v[10:11]
	v_pk_mul_f32 v[20:21], v[8:9], v[8:9]
	s_andn2_b64 vcc, exec, s[72:73]
	s_cbranch_vccnz .Lrope_skip_7
	v_or_b32_e32 v200, 48, v64
	v_mov_b32_e32 v201, s31
	v_cndmask_b32_e64 v200, v200, v201, s[36:37]
	v_lshlrev_b32_e32 v200, 4, v200
	v_and_or_b32 v200, v200, s8, v155
	v_lshlrev_b32_e32 v200, 3, v200
	global_load_dwordx4 v[184:187], v200, s[56:57] offset:32
	global_load_dwordx4 v[188:191], v200, s[56:57] offset:48
	global_load_dwordx4 v[192:195], v200, s[56:57]
	global_load_dwordx4 v[196:199], v200, s[56:57] offset:16
.Lrope_skip_7:
	global_store_dwordx4 v[32:33], v[22:25], off offset:32
	v_cvt_pk_bf16_f32 v31, v26, v27
	v_pk_add_f32 v[16:17], v[16:17], v[16:17] op_sel:[0,1] op_sel_hi:[1,0]
	v_pk_mov_b32 v[22:23], v[20:21], v[18:19] op_sel:[1,0]
	v_mov_b32_e32 v21, v19
	v_pk_add_f32 v[18:19], v[22:23], v[20:21]
	v_pk_mul_f32 v[20:21], v[6:7], v[6:7]
	v_pk_add_f32 v[18:19], v[18:19], v[18:19] op_sel:[0,1] op_sel_hi:[1,0]
	v_pk_mul_f32 v[22:23], v[4:5], v[4:5]
	v_pk_mul_f32 v[24:25], v[2:3], v[2:3]
	v_pk_mul_f32 v[26:27], v[0:1], v[0:1]
	v_add_f32_e32 v22, v22, v23
	v_add_f32_e32 v20, v20, v21
	v_mov_b32_e32 v17, v26
	v_mov_b32_e32 v19, v27
	v_mov_b32_e32 v23, v24
	v_mov_b32_e32 v21, v25
	v_pk_add_f32 v[16:17], v[16:17], v[18:19]
	v_pk_add_f32 v[18:19], v[22:23], v[20:21]
	global_store_dwordx4 v[32:33], v[28:31], off
	v_pk_add_f32 v[16:17], v[16:17], v[18:19]
	s_nop 0
	v_add_f32_e32 v16, v16, v17
	ds_swizzle_b32 v17, v16 offset:swizzle(SWAP,16)
	s_waitcnt lgkmcnt(0)
	v_add_f32_e32 v16, v16, v17
	v_mov_b32_e32 v17, v16
	s_nop 1
	v_permlane32_swap_b32_e32 v16, v17
	v_add_f32_e32 v16, v16, v17
	v_fmamk_f32 v16, v16, 0x3c800000, v221
	v_cmp_gt_f32_e32 vcc, s85, v16
	v_mul_f32_e32 v17, 0x4b800000, v16
	s_nop 0
	v_cndmask_b32_e32 v16, v16, v17, vcc
	v_rsq_f32_e32 v16, v16
	s_nop 0
	v_mul_f32_e32 v17, 0x45800000, v16
	v_cndmask_b32_e32 v16, v16, v17, vcc
	v_mul_f32_e32 v16, v159, v16
	v_pk_mul_f32 v[12:13], v[12:13], v[16:17] op_sel_hi:[1,0]
	v_pk_mul_f32 v[14:15], v[14:15], v[16:17] op_sel_hi:[1,0]
	v_pk_mul_f32 v[8:9], v[8:9], v[16:17] op_sel_hi:[1,0]
	v_pk_mul_f32 v[10:11], v[10:11], v[16:17] op_sel_hi:[1,0]
	v_pk_mul_f32 v[4:5], v[4:5], v[16:17] op_sel_hi:[1,0]
	v_pk_mul_f32 v[6:7], v[6:7], v[16:17] op_sel_hi:[1,0]
	v_pk_mul_f32 v[0:1], v[0:1], v[16:17] op_sel_hi:[1,0]
	v_pk_mul_f32 v[2:3], v[2:3], v[16:17] op_sel_hi:[1,0]
	v_pk_mul_f32 v[14:15], v[110:111], v[14:15]
	v_pk_mul_f32 v[12:13], v[108:109], v[12:13]
	v_pk_mul_f32 v[10:11], v[106:107], v[10:11]
	v_pk_mul_f32 v[8:9], v[104:105], v[8:9]
	v_pk_mul_f32 v[102:103], v[102:103], v[6:7]
	v_pk_mul_f32 v[100:101], v[100:101], v[4:5]
	v_pk_mul_f32 v[98:99], v[98:99], v[2:3]
	v_pk_mul_f32 v[96:97], v[96:97], v[0:1]
	v_or_b32_e32 v0, 48, v64
	s_and_b64 vcc, exec, s[38:39]
	s_cbranch_vccnz .LBB0_265
	v_mov_b32_e32 v1, s31
	v_cndmask_b32_e64 v1, v0, v1, s[36:37]
	v_lshlrev_b32_e32 v1, 4, v1
	v_and_or_b32 v1, v1, s8, v155
	v_lshlrev_b32_e32 v1, 3, v1
	s_waitcnt vmcnt(2)
	v_mov_b32_e32 v2, v184
	v_mov_b32_e32 v3, v185
	v_mov_b32_e32 v4, v186
	v_mov_b32_e32 v5, v187
	v_mov_b32_e32 v16, v188
	v_mov_b32_e32 v17, v189
	v_mov_b32_e32 v18, v190
	v_mov_b32_e32 v19, v191
	v_mov_b32_e32 v20, v192
	v_mov_b32_e32 v21, v193
	v_mov_b32_e32 v22, v194
	v_mov_b32_e32 v23, v195
	v_mov_b32_e32 v24, v196
	v_mov_b32_e32 v25, v197
	v_mov_b32_e32 v26, v198
	v_mov_b32_e32 v27, v199
	s_waitcnt vmcnt(2)
	v_mov_b32_e32 v6, v21
	v_mov_b32_e32 v7, v23
	v_pk_mul_f32 v[30:31], v[100:101], v[6:7]
	v_mov_b32_e32 v21, v22
	s_waitcnt vmcnt(2)
	v_mov_b32_e32 v32, v25
	v_mov_b32_e32 v33, v27
	v_mov_b32_e32 v25, v26
	v_pk_fma_f32 v[26:27], v[12:13], v[20:21], v[30:31] neg_lo:[0,0,1] neg_hi:[0,0,1]
	v_pk_mul_f32 v[20:21], v[100:101], v[20:21]
	v_pk_mul_f32 v[28:29], v[102:103], v[32:33]
	v_pk_mul_f32 v[22:23], v[102:103], v[24:25]
	v_pk_fma_f32 v[100:101], v[12:13], v[6:7], v[20:21]
	v_mov_b32_e32 v12, v3
	v_mov_b32_e32 v13, v5
	v_mov_b32_e32 v20, v17
	v_mov_b32_e32 v21, v19
	v_pk_fma_f32 v[28:29], v[14:15], v[24:25], v[28:29] neg_lo:[0,0,1] neg_hi:[0,0,1]
	v_pk_fma_f32 v[102:103], v[14:15], v[32:33], v[22:23]
	v_pk_mul_f32 v[14:15], v[96:97], v[12:13]
	v_pk_mul_f32 v[6:7], v[98:99], v[20:21]
	v_mov_b32_e32 v17, v18
	v_mov_b32_e32 v3, v4
	v_pk_fma_f32 v[6:7], v[10:11], v[16:17], v[6:7] neg_lo:[0,0,1] neg_hi:[0,0,1]
	v_pk_fma_f32 v[4:5], v[8:9], v[2:3], v[14:15] neg_lo:[0,0,1] neg_hi:[0,0,1]
	v_pk_mul_f32 v[2:3], v[96:97], v[2:3]
	v_pk_mul_f32 v[14:15], v[98:99], v[16:17]
	v_pk_fma_f32 v[96:97], v[8:9], v[12:13], v[2:3]
	v_pk_fma_f32 v[98:99], v[10:11], v[20:21], v[14:15]
	v_mov_b64_e32 v[10:11], v[6:7]
	v_mov_b64_e32 v[12:13], v[26:27]
	v_mov_b64_e32 v[8:9], v[4:5]
	v_mov_b64_e32 v[14:15], v[28:29]
